# addon_dpp_row_reduction
# speedup vs baseline: 1.0060x; 1.0006x over previous
; __device__ __forceinline__ unsigned cvt_pk_bf16(float lo, float hi) { const f32x2_t v = {lo, hi}; const bf16x2_t r = __builtin_convertvector(v, bf16x2_t); return __builtin_bit_cast(unsigned, r); }
; __device__ __forceinline__ void p0_proc4(bf16_t* XB, int m0, int NGW, int lane, const f32x4 (&v)[4][4]) {
;     float s[4];
; #pragma unroll
;     for (int u = 0; u < 4; ++u) { float t = 0.f;
; #pragma unroll
;         for (int j = 0; j < 4; ++j) t += (v[u][j][0] * v[u][j][0] + v[u][j][1] * v[u][j][1]) + (v[u][j][2] * v[u][j][2] + v[u][j][3] * v[u][j][3]);
;         s[u] = t; }
; #pragma unroll
;     for (int o = 1; o < 64; o <<= 1) {
; #pragma unroll
;         for (int u = 0; u < 4; ++u) s[u] += __shfl_xor(s[u], o); }
; #pragma unroll
;     for (int u = 0; u < 4; ++u) { const int m = m0 + u * NGW; if (m >= T) break;
;         const float rstd = 1.0f / sqrtf(s[u] * (1.0f / 1024.0f) + NORM_EPS);
;         u32x2* o8 = (u32x2*)(XB + (size_t)m * 1024) + lane;
; #pragma unroll
;         for (int j = 0; j < 4; ++j) { u32x2 w; w.x = cvt_pk_bf16(v[u][j][0] * rstd, v[u][j][1] * rstd); w.y = cvt_pk_bf16(v[u][j][2] * rstd, v[u][j][3] * rstd); o8[64 * j] = w; } }
.LBB0_208:
	s_cmp_eq_u32 s98, -1
	s_cbranch_scc1 .Lax_done
	s_waitcnt vmcnt(16)
	v_mul_f32_e32 v203, v232, v232
	v_mul_f32_e32 v204, v234, v234
	v_fmac_f32_e32 v203, v233, v233
	v_fmac_f32_e32 v204, v235, v235
	v_add_f32_e32 v203, v203, v204
	v_mov_b32_e32 v201, v203
	v_mul_f32_e32 v203, v236, v236
	v_mul_f32_e32 v204, v238, v238
	v_fmac_f32_e32 v203, v237, v237
	v_fmac_f32_e32 v204, v239, v239
	v_add_f32_e32 v203, v203, v204
	v_add_f32_e32 v201, v201, v203
	v_mul_f32_e32 v203, v240, v240
	v_mul_f32_e32 v204, v242, v242
	v_fmac_f32_e32 v203, v241, v241
	v_fmac_f32_e32 v204, v243, v243
	v_add_f32_e32 v203, v203, v204
	v_add_f32_e32 v201, v201, v203
	v_mul_f32_e32 v203, v244, v244
	v_mul_f32_e32 v204, v246, v246
	v_fmac_f32_e32 v203, v245, v245
	v_fmac_f32_e32 v204, v247, v247
	v_add_f32_e32 v203, v203, v204
	v_add_f32_e32 v201, v201, v203
	v_mul_f32_e32 v205, v182, v182
	v_mul_f32_e32 v206, v184, v184
	v_fmac_f32_e32 v205, v183, v183
	v_fmac_f32_e32 v206, v185, v185
	v_add_f32_e32 v205, v205, v206
	v_mov_b32_e32 v202, v205
	v_mul_f32_e32 v205, v250, v250
	v_mul_f32_e32 v206, v252, v252
	v_fmac_f32_e32 v205, v251, v251
	v_fmac_f32_e32 v206, v253, v253
	v_add_f32_e32 v205, v205, v206
	v_add_f32_e32 v202, v202, v205
	v_mul_f32_e32 v205, v178, v178
	v_mul_f32_e32 v206, v180, v180
	v_fmac_f32_e32 v205, v179, v179
	v_fmac_f32_e32 v206, v181, v181
	v_add_f32_e32 v205, v205, v206
	v_add_f32_e32 v202, v202, v205
	v_mul_f32_e32 v205, v154, v154
	v_mul_f32_e32 v206, v156, v156
	v_fmac_f32_e32 v205, v155, v155
	v_fmac_f32_e32 v206, v157, v157
	v_add_f32_e32 v205, v205, v206
	v_add_f32_e32 v202, v202, v205
	v_lshrrev_b32_e32 v210, 2, v254
	s_nop 0
	v_add_f32_dpp v201, v201, v201 quad_perm:[1,0,3,2] row_mask:0xf bank_mask:0xf
	v_add_f32_dpp v202, v202, v202 quad_perm:[1,0,3,2] row_mask:0xf bank_mask:0xf
	s_nop 0
	v_add_f32_dpp v201, v201, v201 quad_perm:[2,3,0,1] row_mask:0xf bank_mask:0xf
	v_add_f32_dpp v202, v202, v202 quad_perm:[2,3,0,1] row_mask:0xf bank_mask:0xf
	s_nop 0
	v_add_f32_dpp v201, v201, v201 row_half_mirror row_mask:0xf bank_mask:0xf
	v_add_f32_dpp v202, v202, v202 row_half_mirror row_mask:0xf bank_mask:0xf
	s_nop 0
	v_add_f32_dpp v201, v201, v201 row_mirror row_mask:0xf bank_mask:0xf
	v_add_f32_dpp v202, v202, v202 row_mirror row_mask:0xf bank_mask:0xf
	v_xor_b32_e32 v211, 64, v210
	ds_bpermute_b32 v207, v211, v201
	ds_bpermute_b32 v208, v211, v202
	s_waitcnt lgkmcnt(0)
	v_add_f32_e32 v201, v201, v207
	v_add_f32_e32 v202, v202, v208
	v_xor_b32_e32 v211, 128, v210
	ds_bpermute_b32 v207, v211, v201
	ds_bpermute_b32 v208, v211, v202
	s_waitcnt lgkmcnt(0)
	v_add_f32_e32 v201, v201, v207
	v_add_f32_e32 v202, v202, v208
	v_mov_b32_e32 v212, 0x358637bd
	s_nop 0
	v_fmamk_f32 v213, v201, 0x3a800000, v212
	v_fmamk_f32 v214, v202, 0x3a800000, v212
	v_rsq_f32_e32 v215, v213
	v_rsq_f32_e32 v216, v214
	s_nop 0
	v_mul_f32_e32 v217, v213, v215
	v_mul_f32_e32 v218, v214, v216
	v_fma_f32 v217, -v217, v215, 1.0
	v_fma_f32 v218, -v218, v216, 1.0
	v_mul_f32_e32 v219, 0.5, v215
	v_mul_f32_e32 v220, 0.5, v216
	v_fma_f32 v222, v219, v217, v215
	v_fma_f32 v224, v220, v218, v216
	s_lshl_b32 s100, s98, 11
	s_add_u32 s100, s100, s64
	s_addc_u32 s101, s65, 0
	s_add_u32 s100, s100, 0x1100000
	s_addc_u32 s101, s101, 0
	v_lshrrev_b32_e32 v221, 1, v254
	s_cmp_eq_u32 s32, 1
	s_cbranch_scc0 .Lax_wt
	v_pk_mul_f32 v[226:227], v[232:233], v[222:223] op_sel_hi:[1,0]
	v_pk_mul_f32 v[228:229], v[234:235], v[222:223] op_sel_hi:[1,0]
	v_cvt_pk_bf16_f32 v230, v226, v227
	v_cvt_pk_bf16_f32 v231, v228, v229
	global_store_dwordx2 v221, v[230:231], s[100:101] offset:0
	v_pk_mul_f32 v[226:227], v[236:237], v[222:223] op_sel_hi:[1,0]
	v_pk_mul_f32 v[228:229], v[238:239], v[222:223] op_sel_hi:[1,0]
	v_cvt_pk_bf16_f32 v202, v226, v227
	v_cvt_pk_bf16_f32 v203, v228, v229
	global_store_dwordx2 v221, v[202:203], s[100:101] offset:512
	v_pk_mul_f32 v[226:227], v[240:241], v[222:223] op_sel_hi:[1,0]
	v_pk_mul_f32 v[228:229], v[242:243], v[222:223] op_sel_hi:[1,0]
	v_cvt_pk_bf16_f32 v230, v226, v227
	v_cvt_pk_bf16_f32 v231, v228, v229
	global_store_dwordx2 v221, v[230:231], s[100:101] offset:1024
	v_pk_mul_f32 v[226:227], v[244:245], v[222:223] op_sel_hi:[1,0]
	v_pk_mul_f32 v[228:229], v[246:247], v[222:223] op_sel_hi:[1,0]
	v_cvt_pk_bf16_f32 v202, v226, v227
	v_cvt_pk_bf16_f32 v203, v228, v229
	global_store_dwordx2 v221, v[202:203], s[100:101] offset:1536
	v_pk_mul_f32 v[226:227], v[182:183], v[224:225] op_sel_hi:[1,0]
	v_pk_mul_f32 v[228:229], v[184:185], v[224:225] op_sel_hi:[1,0]
	v_cvt_pk_bf16_f32 v230, v226, v227
	v_cvt_pk_bf16_f32 v231, v228, v229
	global_store_dwordx2 v221, v[230:231], s[100:101] offset:2048
	v_pk_mul_f32 v[226:227], v[250:251], v[224:225] op_sel_hi:[1,0]
	v_pk_mul_f32 v[228:229], v[252:253], v[224:225] op_sel_hi:[1,0]
	v_cvt_pk_bf16_f32 v202, v226, v227
	v_cvt_pk_bf16_f32 v203, v228, v229
	global_store_dwordx2 v221, v[202:203], s[100:101] offset:2560
	v_pk_mul_f32 v[226:227], v[178:179], v[224:225] op_sel_hi:[1,0]
	v_pk_mul_f32 v[228:229], v[180:181], v[224:225] op_sel_hi:[1,0]
	v_cvt_pk_bf16_f32 v230, v226, v227
	v_cvt_pk_bf16_f32 v231, v228, v229
	global_store_dwordx2 v221, v[230:231], s[100:101] offset:3072
	v_pk_mul_f32 v[226:227], v[154:155], v[224:225] op_sel_hi:[1,0]
	v_pk_mul_f32 v[228:229], v[156:157], v[224:225] op_sel_hi:[1,0]
	v_cvt_pk_bf16_f32 v202, v226, v227
	v_cvt_pk_bf16_f32 v203, v228, v229
	global_store_dwordx2 v221, v[202:203], s[100:101] offset:3584
	s_branch .Lax_stdone
